# v29: v28 but P4 conversion balanced: each workgroup converts its own share, odd workgroups before their GEMM tiles, even workgroups after them
# speedup vs baseline: 1.0118x; 1.0032x over previous
; __device__ __forceinline__ unsigned pk2(float lo, float hi) { return f2bf(lo) | (f2bf(hi) << 16); }
; __global__ void __launch_bounds__(NWAVES * 64, 2) fwd_megakernel(Args args) {
;     ...
;         for (int m0 = gw * 4; m0 < MP; m0 += NGW * 4) {
;             f32x4 v[4];
; #pragma unroll
;             for (int q = 0; q < 4; ++q) v[q] = __builtin_nontemporal_load((const f32x4*)(p_prompt + (size_t)(m0 + q) * 256) + lane);
; #pragma unroll
;             for (int q = 0; q < 4; ++q) { u32x2 w; w.x = pk2(v[q][0], v[q][1]); w.y = pk2(v[q][2], v[q][3]); *((u32x2*)(HP + (size_t)(m0 + q) * LDHP + 1024) + lane) = w; }
;         }
.Lp4t_skip:
	s_cmpk_gt_i32 s3, 0x1fff
	s_cbranch_scc1 .LBB0_881
	s_bitcmp1_b32 s94, 0
	s_cbranch_scc0 .LBB0_881
	s_mov_b32 s40, s3
	s_mov_b32 s41, 1
.Lp4c_pass:
	s_lshl_b32 s4, s40, 2
	s_lshl_b32 s0, s93, 5
	s_ashr_i32 s5, s4, 31
	s_mul_i32 s1, s40, 0x2800
	s_mul_hi_i32 s7, s4, 0xa00
	s_add_u32 s6, s62, s1
	s_addc_u32 s7, s63, s7
	s_ashr_i32 s1, s0, 31
	s_lshl_b64 s[8:9], s[4:5], 10
	v_mov_b32_e32 v5, 0
	s_add_u32 s8, s76, s8
	v_mov_b32_e32 v3, v5
	s_addc_u32 s9, s77, s9
	v_lshl_add_u64 v[6:7], s[6:7], 0, v[4:5]
	s_mov_b64 s[6:7], 0x5a00800
	v_lshl_add_u64 v[8:9], s[8:9], 0, v[2:3]
	s_mov_b64 s[8:9], 0xc00
	v_lshl_add_u64 v[6:7], v[6:7], 0, s[6:7]
	s_mul_i32 s6, s93, 0x14000
	s_mul_hi_i32 s7, s0, 0xa00
	v_lshl_add_u64 v[8:9], v[8:9], 0, s[8:9]
	s_lshl_b64 s[8:9], s[0:1], 10
	s_movk_i32 s1, 0x7fff
	s_mov_b32 s5, 0xffff0000
	s_movk_i32 s10, 0x1000
	s_mul_i32 s11, s0, 3
	s_add_i32 s11, s11, s4
	s_cmp_lt_i32 s11, 0x8000
	s_mov_b32 s11, 0
	s_cbranch_scc0 .LBB0_880
	v_lshl_add_u64 v[74:75], v[8:9], 0, s[8:9]
	v_lshl_add_u64 v[76:77], v[74:75], 0, s[8:9]
	v_lshl_add_u64 v[78:79], v[76:77], 0, s[8:9]
	global_load_dwordx4 v[10:13], v[8:9], off offset:-3072 nt
	global_load_dwordx4 v[14:17], v[8:9], off offset:-2048 nt
	global_load_dwordx4 v[18:21], v[8:9], off offset:-1024 nt
	global_load_dwordx4 v[22:25], v[8:9], off nt
	global_load_dwordx4 v[26:29], v[74:75], off offset:-3072 nt
	global_load_dwordx4 v[30:33], v[74:75], off offset:-2048 nt
	global_load_dwordx4 v[34:37], v[74:75], off offset:-1024 nt
	global_load_dwordx4 v[38:41], v[74:75], off nt
	global_load_dwordx4 v[42:45], v[76:77], off offset:-3072 nt
	global_load_dwordx4 v[46:49], v[76:77], off offset:-2048 nt
	global_load_dwordx4 v[50:53], v[76:77], off offset:-1024 nt
	global_load_dwordx4 v[54:57], v[76:77], off nt
	global_load_dwordx4 v[58:61], v[78:79], off offset:-3072 nt
	global_load_dwordx4 v[62:65], v[78:79], off offset:-2048 nt
	global_load_dwordx4 v[66:69], v[78:79], off offset:-1024 nt
	global_load_dwordx4 v[70:73], v[78:79], off nt
	v_lshl_add_u64 v[80:81], v[6:7], 0, s[10:11]
	s_waitcnt vmcnt(15)
	v_cvt_pk_bf16_f32 v82, v10, v11
	v_cvt_pk_bf16_f32 v83, v12, v13
	global_store_dwordx2 v[6:7], v[82:83], off
	s_waitcnt vmcnt(15)
	v_cvt_pk_bf16_f32 v84, v14, v15
	v_cvt_pk_bf16_f32 v85, v16, v17
	global_store_dwordx2 v[6:7], v[84:85], off offset:2560
	s_waitcnt vmcnt(15)
	v_cvt_pk_bf16_f32 v82, v18, v19
	v_cvt_pk_bf16_f32 v83, v20, v21
	global_store_dwordx2 v[80:81], v[82:83], off offset:1024
	s_waitcnt vmcnt(15)
	v_cvt_pk_bf16_f32 v84, v22, v23
	v_cvt_pk_bf16_f32 v85, v24, v25
	global_store_dwordx2 v[80:81], v[84:85], off offset:3584
	v_lshl_add_u64 v[6:7], v[6:7], 0, s[6:7]
	v_lshl_add_u64 v[80:81], v[6:7], 0, s[10:11]
	s_waitcnt vmcnt(15)
	v_cvt_pk_bf16_f32 v82, v26, v27
	v_cvt_pk_bf16_f32 v83, v28, v29
	global_store_dwordx2 v[6:7], v[82:83], off
	s_waitcnt vmcnt(15)
	v_cvt_pk_bf16_f32 v84, v30, v31
	v_cvt_pk_bf16_f32 v85, v32, v33
	global_store_dwordx2 v[6:7], v[84:85], off offset:2560
	s_waitcnt vmcnt(15)
	v_cvt_pk_bf16_f32 v82, v34, v35
	v_cvt_pk_bf16_f32 v83, v36, v37
	global_store_dwordx2 v[80:81], v[82:83], off offset:1024
	s_waitcnt vmcnt(15)
	v_cvt_pk_bf16_f32 v84, v38, v39
	v_cvt_pk_bf16_f32 v85, v40, v41
	global_store_dwordx2 v[80:81], v[84:85], off offset:3584
	v_lshl_add_u64 v[6:7], v[6:7], 0, s[6:7]
	v_lshl_add_u64 v[80:81], v[6:7], 0, s[10:11]
	s_waitcnt vmcnt(15)
	v_cvt_pk_bf16_f32 v82, v42, v43
	v_cvt_pk_bf16_f32 v83, v44, v45
	global_store_dwordx2 v[6:7], v[82:83], off
	s_waitcnt vmcnt(15)
	v_cvt_pk_bf16_f32 v84, v46, v47
	v_cvt_pk_bf16_f32 v85, v48, v49
	global_store_dwordx2 v[6:7], v[84:85], off offset:2560
	s_waitcnt vmcnt(15)
	v_cvt_pk_bf16_f32 v82, v50, v51
	v_cvt_pk_bf16_f32 v83, v52, v53
	global_store_dwordx2 v[80:81], v[82:83], off offset:1024
	s_waitcnt vmcnt(15)
	v_cvt_pk_bf16_f32 v84, v54, v55
	v_cvt_pk_bf16_f32 v85, v56, v57
	global_store_dwordx2 v[80:81], v[84:85], off offset:3584
	v_lshl_add_u64 v[6:7], v[6:7], 0, s[6:7]
	v_lshl_add_u64 v[80:81], v[6:7], 0, s[10:11]
	s_waitcnt vmcnt(15)
	v_cvt_pk_bf16_f32 v82, v58, v59
	v_cvt_pk_bf16_f32 v83, v60, v61
	global_store_dwordx2 v[6:7], v[82:83], off
	s_waitcnt vmcnt(15)
	v_cvt_pk_bf16_f32 v84, v62, v63
	v_cvt_pk_bf16_f32 v85, v64, v65
	global_store_dwordx2 v[6:7], v[84:85], off offset:2560
	s_waitcnt vmcnt(15)
	v_cvt_pk_bf16_f32 v82, v66, v67
	v_cvt_pk_bf16_f32 v83, v68, v69
	global_store_dwordx2 v[80:81], v[82:83], off offset:1024
	s_waitcnt vmcnt(15)
	v_cvt_pk_bf16_f32 v84, v70, v71
	v_cvt_pk_bf16_f32 v85, v72, v73
	global_store_dwordx2 v[80:81], v[84:85], off offset:3584
	s_add_i32 s40, s40, 8
	s_add_i32 s41, s41, 1
	s_cmp_lt_u32 s41, 2
	s_cbranch_scc1 .Lp4c_pass
	s_cmp_eq_u32 s41, 4
	s_cbranch_scc1 .Lp4c_ret
	s_branch .LBB0_881

; #define PG8_WAIT_V(n) asm volatile("s_waitcnt vmcnt(" #n ")" ::: "memory")
; #define PG8_BAR __builtin_amdgcn_s_barrier()
; __device__ __forceinline__ unsigned pk2(float lo, float hi) { return f2bf(lo) | (f2bf(hi) << 16); }
; template <class Epi, int AC0, int BC0, int NT0, int AC1, int BC1, int NT1>
; __device__ __forceinline__ void gemm_phase(LAS unsigned char* lds, const Gemm g, const StaticOrder& S, const Epi& E, int tid) {
;     ...
;     PG8_WAIT_V(0);
;     PG8_BAR;
; __global__ void __launch_bounds__(NWAVES * 64, 2) fwd_megakernel(Args args) {
;     ...
;         for (int m0 = gw * 4; m0 < MP; m0 += NGW * 4) {
;             f32x4 v[4];
; #pragma unroll
;             for (int q = 0; q < 4; ++q) v[q] = __builtin_nontemporal_load((const f32x4*)(p_prompt + (size_t)(m0 + q) * 256) + lane);
; #pragma unroll
;             for (int q = 0; q < 4; ++q) { u32x2 w; w.x = pk2(v[q][0], v[q][1]); w.y = pk2(v[q][2], v[q][3]); *((u32x2*)(HP + (size_t)(m0 + q) * LDHP + 1024) + lane) = w; }
;         }
.LBB0_921:
	s_waitcnt vmcnt(0)
	s_bitcmp1_b32 s94, 0
	s_cbranch_scc1 .Lp4c_skip2
	s_mov_b64 s[42:43], s[8:9]
	v_mov_b32_e32 v86, v5
	v_readlane_b32 s0, v254, 0
	v_readlane_b32 s1, v254, 1
	s_sub_u32 s0, s0, 0xc0
	s_subb_u32 s1, s1, 0
	s_load_dwordx2 s[76:77], s[0:1], 0x30
	v_readfirstlane_b32 s40, v0
	s_ashr_i32 s40, s40, 6
	v_readlane_b32 s41, v254, 6
	s_add_i32 s40, s40, s41
	v_and_b32_e32 v2, 63, v0
	v_lshlrev_b32_e32 v4, 3, v2
	v_lshlrev_b32_e32 v2, 4, v2
	s_mov_b32 s41, 3
	s_waitcnt lgkmcnt(0)
	s_branch .Lp4c_pass
.Lp4c_ret:
	s_waitcnt vmcnt(0)
	s_mov_b64 s[8:9], s[42:43]
	v_mov_b32_e32 v5, v86
.Lp4c_skip2:
	v_readlane_b32 s54, v254, 2
	v_readlane_b32 s20, v254, 4
	v_readlane_b32 s55, v254, 3
	v_readlane_b32 s21, v254, 5
	s_barrier
